# W_up sample-tile epilogue: SS words and conv-state pieces loaded up front (was 16 serialized round trips)
# baseline (speedup 1.0000x reference)
; __device__ __forceinline__ unsigned cvt_pk_bf16(float lo, float hi) { unsigned r; asm volatile("v_cvt_pk_bf16_f32 %0, %1, %2" : "=v"(r) : "v"(lo), "v"(hi)); return r; }
; __device__ __forceinline__ float silu_f(float x) { return x * __builtin_amdgcn_rcpf(1.f + __expf(-x)); }
;     __device__ __forceinline__ void operator()(const f32x4 (&acc)[2][2][4][2], const pg8::Unit& u, int wr, int wc, int fr, int fq) const {
;     ...
;         if (u.pm == 32) {
;             if (!RUN_FIX) __builtin_amdgcn_s_barrier();
; #pragma unroll
;             for (int n = 0; n < 2; ++n) { const int cn = col + 4 * n;
;                 const f32x4 w0 = *(const f32x4*)(cw + cn), w1 = *(const f32x4*)(cw + DFF + cn), w2 = *(const f32x4*)(cw + 2 * DFF + cn), bb = *(const f32x4*)(cb + cn);
; #pragma unroll
;                 for (int m = 0; m < 4; ++m) { const int s = wr * 64 + m * 16 + fr; const float* sp = st_in + (size_t)s * 2 * DFF + cn; float* op = ffn_s + (size_t)s * 2 * DFF + cn;
;                     const float r1 = rsqrtf(SS[MP + s] * (1.f / DM) + EPS);
;                     const f32x4 s0 = *(const f32x4*)sp, s1 = *(const f32x4*)(sp + DFF), uu = acc[0][0][m][n] * r1, vv = acc[0][1][m][n] * r1;
;                     *(f32x4*)op = s1; *(f32x4*)(op + DFF) = uu;
;                     const f32x4 cu = s0 * w0 + s1 * w1 + uu * w2 + bb; u32x2 hw;
;                     hw.x = cvt_pk_bf16(silu_f(cu[0]) * vv[0], silu_f(cu[1]) * vv[1]); hw.y = cvt_pk_bf16(silu_f(cu[2]) * vv[2], silu_f(cu[3]) * vv[3]);
;                     *(u32x2*)(H + (size_t)(MP + s) * DFF + cn) = hw; *(u32x2*)(H + (size_t)(MP + 128 + s) * DFF + cn) = (u32x2){0u, 0u}; }
.LBB0_815:
	s_and_b64 vcc, exec, s[6:7]
	s_cbranch_vccz .LBB0_814
	v_add_u32_e32 v84, 0x2000, v229
	v_ashrrev_i32_e32 v85, 31, v84
	v_lshl_add_u64 v[86:87], v[84:85], 2, s[62:63]
	s_barrier
	v_mul_u32_u24_e32 v208, 0xb000, v229
	v_lshl_add_u32 v208, v186, 2, v208
	v_lshlrev_b32_e32 v209, 2, v229
	s_add_u32 s98, s62, 0x8000
	s_addc_u32 s99, s63, 0
	global_load_dword v214, v209, s[98:99]
	global_load_dword v215, v209, s[98:99] offset:64
	global_load_dword v216, v209, s[98:99] offset:128
	global_load_dword v219, v209, s[98:99] offset:192
	s_mov_b64 s[98:99], s[56:57]
	s_add_u32 s100, s98, s16
	s_addc_u32 s101, s99, 0
	global_load_dwordx4 v[130:133], v208, s[98:99]
	global_load_dwordx4 v[134:137], v208, s[100:101] offset:2048
	global_load_dwordx4 v[164:167], v208, s[98:99] offset:16
	global_load_dwordx4 v[188:191], v208, s[100:101] offset:2064
	s_add_u32 s98, s98, 0xb0000
	s_addc_u32 s99, s99, 0
	s_add_u32 s100, s98, s16
	s_addc_u32 s101, s99, 0
	global_load_dwordx4 v[138:141], v208, s[98:99]
	global_load_dwordx4 v[142:145], v208, s[100:101] offset:2048
	global_load_dwordx4 v[192:195], v208, s[98:99] offset:16
	global_load_dwordx4 v[196:199], v208, s[100:101] offset:2064
	s_add_u32 s98, s98, 0xb0000
	s_addc_u32 s99, s99, 0
	s_add_u32 s100, s98, s16
	s_addc_u32 s101, s99, 0
	global_load_dwordx4 v[146:149], v208, s[98:99]
	global_load_dwordx4 v[150:153], v208, s[100:101] offset:2048
	global_load_dwordx4 v[200:203], v208, s[98:99] offset:16
	global_load_dwordx4 v[204:207], v208, s[100:101] offset:2064
	s_add_u32 s98, s98, 0xb0000
	s_addc_u32 s99, s99, 0
	s_add_u32 s100, s98, s16
	s_addc_u32 s101, s99, 0
	global_load_dwordx4 v[154:157], v208, s[98:99]
	global_load_dwordx4 v[160:163], v208, s[100:101] offset:2048
	global_load_dwordx4 v[248:251], v208, s[98:99] offset:16
	global_load_dwordx4 v[252:255], v208, s[100:101] offset:2064
	v_ashrrev_i32_e32 v187, 31, v186
	v_mov_b64_e32 v[112:113], s[56:57]
	s_mov_b32 s25, 0xb000
	v_lshlrev_b64 v[118:119], 2, v[186:187]
	v_mad_i64_i32 v[80:81], s[6:7], v229, s25, v[112:113]
	v_lshl_add_u64 v[82:83], v[80:81], 0, v[118:119]
	v_lshl_add_u64 v[68:69], s[34:35], 0, v[118:119]
	v_lshl_add_u64 v[100:101], s[26:27], 0, v[118:119]
	global_load_dwordx4 v[76:79], v[68:69], off
	global_load_dwordx4 v[64:67], v[100:101], off
	v_lshl_add_u64 v[68:69], s[22:23], 0, v[118:119]
	v_lshl_add_u64 v[98:99], s[38:39], 0, v[118:119]
	global_load_dwordx4 v[68:71], v[68:69], off
	v_mov_b64_e32 v[120:121], s[60:61]
	global_load_dwordx4 v[72:75], v[98:99], off
	v_mad_i64_i32 v[80:81], s[6:7], v229, s25, v[120:121]
	v_lshl_add_u64 v[80:81], v[80:81], 0, v[118:119]
	v_mov_b64_e32 v[114:115], s[4:5]
	v_lshlrev_b64 v[116:117], 1, v[186:187]
	s_mov_b32 s10, s11
	v_mov_b64_e32 v[124:125], s[10:11]
	v_add_u32_e32 v110, 0x2020, v229
	v_ashrrev_i32_e32 v111, 31, v110
	s_waitcnt vmcnt(0)
	v_mov_b32_e32 v85, v214
	v_mov_b32_e32 v90, v130
	v_mov_b32_e32 v91, v131
	v_mov_b32_e32 v92, v132
	v_mov_b32_e32 v93, v133
	v_fmamk_f32 v85, v85, 0x3a000000, v212
	v_cmp_gt_f32_e32 vcc, s14, v85
	v_mul_f32_e32 v88, 0x4b800000, v85
	s_nop 0
	v_cndmask_b32_e32 v85, v85, v88, vcc
	v_rsq_f32_e32 v85, v85
	s_nop 0
	v_mul_f32_e32 v88, 0x45800000, v85
	v_cndmask_b32_e32 v106, v85, v88, vcc
	v_add_co_u32_e32 v88, vcc, s16, v82
	v_pk_mul_f32 v[102:103], v[60:61], v[106:107] op_sel_hi:[1,0]
	s_nop 0
	v_addc_co_u32_e32 v89, vcc, 0, v83, vcc
	v_mov_b32_e32 v94, v134
	v_mov_b32_e32 v95, v135
	v_mov_b32_e32 v96, v136
	v_mov_b32_e32 v97, v137
	v_pk_mul_f32 v[56:57], v[56:57], v[106:107] op_sel_hi:[1,0]
	v_pk_mul_f32 v[104:105], v[62:63], v[106:107] op_sel_hi:[1,0]
	v_add_co_u32_e32 v60, vcc, s16, v80
	v_pk_mul_f32 v[58:59], v[58:59], v[106:107] op_sel_hi:[1,0]
	s_nop 0
	v_addc_co_u32_e32 v61, vcc, 0, v81, vcc
	global_store_dwordx4 v[60:61], v[102:105], off offset:2048
	global_store_dwordx4 v[80:81], v[94:97], off
	s_nop 1
	v_pk_mul_f32 v[94:95], v[76:77], v[94:95]
	v_pk_mul_f32 v[62:63], v[78:79], v[96:97]
	v_pk_fma_f32 v[90:91], v[64:65], v[90:91], v[94:95]
	v_pk_fma_f32 v[62:63], v[66:67], v[92:93], v[62:63]
	v_pk_fma_f32 v[90:91], v[68:69], v[102:103], v[90:91]
	v_pk_fma_f32 v[62:63], v[70:71], v[104:105], v[62:63]
	v_pk_add_f32 v[90:91], v[72:73], v[90:91]
	v_pk_add_f32 v[62:63], v[74:75], v[62:63]
	v_mul_f32_e32 v85, 0xbfb8aa3b, v90
	v_exp_f32_e32 v85, v85
	v_add_u32_e32 v104, 0x2010, v229
	v_ashrrev_i32_e32 v105, 31, v104
	v_lshl_add_u64 v[94:95], v[104:105], 2, s[62:63]
	v_add_f32_e32 v85, 1.0, v85
	v_rcp_f32_e32 v85, v85
	s_nop 0
	v_mul_f32_e32 v85, v90, v85
	v_mul_f32_e32 v56, v56, v85
	v_mul_f32_e32 v85, 0xbfb8aa3b, v91
	v_exp_f32_e32 v85, v85
	s_nop 0
	v_add_f32_e32 v85, 1.0, v85
	v_rcp_f32_e32 v85, v85
	s_nop 0
	v_mul_f32_e32 v85, v91, v85
	v_mul_f32_e32 v57, v57, v85
	v_cvt_pk_bf16_f32 v56, v56, v57
	v_mul_f32_e32 v57, 0xbfb8aa3b, v62
	v_exp_f32_e32 v57, v57
	s_nop 0
	v_add_f32_e32 v57, 1.0, v57
	v_rcp_f32_e32 v57, v57
	s_nop 0
	v_mul_f32_e32 v57, v62, v57
	v_mul_f32_e32 v57, v58, v57
	v_mul_f32_e32 v58, 0xbfb8aa3b, v63
	v_exp_f32_e32 v58, v58
	s_nop 0
	v_add_f32_e32 v58, 1.0, v58
	v_rcp_f32_e32 v58, v58
	s_nop 0
	v_mul_f32_e32 v58, v63, v58
	v_mul_f32_e32 v58, v59, v58
	v_cvt_pk_bf16_f32 v57, v57, v58
	v_mad_i64_i32 v[58:59], s[6:7], v84, s71, v[114:115]
	v_lshl_add_u64 v[84:85], v[58:59], 0, v[116:117]
	global_store_dwordx2 v[84:85], v[56:57], off
	v_add_u32_e32 v56, 0x2080, v229
	v_mad_i64_i32 v[56:57], s[6:7], v56, s71, v[114:115]
	v_add_u32_e32 v58, 16, v229
	v_lshl_add_u64 v[90:91], v[56:57], 0, v[116:117]
	v_mad_i64_i32 v[56:57], s[6:7], v58, s25, v[112:113]
	global_store_dwordx2 v[90:91], v[124:125], off
	v_lshl_add_u64 v[92:93], v[56:57], 0, v[118:119]
; __device__ __forceinline__ unsigned cvt_pk_bf16(float lo, float hi) { unsigned r; asm volatile("v_cvt_pk_bf16_f32 %0, %1, %2" : "=v"(r) : "v"(lo), "v"(hi)); return r; }
; __device__ __forceinline__ float silu_f(float x) { return x * __builtin_amdgcn_rcpf(1.f + __expf(-x)); }
;     __device__ __forceinline__ void operator()(const f32x4 (&acc)[2][2][4][2], const pg8::Unit& u, int wr, int wc, int fr, int fq) const {
;     ...
;                 for (int m = 0; m < 4; ++m) { const int s = wr * 64 + m * 16 + fr; const float* sp = st_in + (size_t)s * 2 * DFF + cn; float* op = ffn_s + (size_t)s * 2 * DFF + cn;
;                     const float r1 = rsqrtf(SS[MP + s] * (1.f / DM) + EPS);
;                     const f32x4 s0 = *(const f32x4*)sp, s1 = *(const f32x4*)(sp + DFF), uu = acc[0][0][m][n] * r1, vv = acc[0][1][m][n] * r1;
;                     *(f32x4*)op = s1; *(f32x4*)(op + DFF) = uu;
;                     const f32x4 cu = s0 * w0 + s1 * w1 + uu * w2 + bb; u32x2 hw;
;                     hw.x = cvt_pk_bf16(silu_f(cu[0]) * vv[0], silu_f(cu[1]) * vv[1]); hw.y = cvt_pk_bf16(silu_f(cu[2]) * vv[2], silu_f(cu[3]) * vv[3]);
;                     *(u32x2*)(H + (size_t)(MP + s) * DFF + cn) = hw; *(u32x2*)(H + (size_t)(MP + 128 + s) * DFF + cn) = (u32x2){0u, 0u}; }
	v_mad_i64_i32 v[56:57], s[6:7], v58, s25, v[120:121]
	v_lshl_add_u64 v[62:63], v[56:57], 0, v[118:119]
	v_mov_b32_e32 v56, v215
	v_fmamk_f32 v56, v56, 0x3a000000, v212
	v_cmp_gt_f32_e32 vcc, s14, v56
	v_mul_f32_e32 v57, 0x4b800000, v56
	s_nop 0
	v_cndmask_b32_e32 v56, v56, v57, vcc
	v_rsq_f32_e32 v56, v56
	s_nop 0
	v_mul_f32_e32 v57, 0x45800000, v56
	v_cndmask_b32_e32 v102, v56, v57, vcc
	v_add_co_u32_e32 v96, vcc, s16, v92
	v_mov_b32_e32 v56, v138
	v_mov_b32_e32 v57, v139
	v_mov_b32_e32 v58, v140
	v_mov_b32_e32 v59, v141
	s_nop 0
	v_addc_co_u32_e32 v97, vcc, 0, v93, vcc
	v_mov_b32_e32 v106, v142
	v_mov_b32_e32 v107, v143
	v_mov_b32_e32 v108, v144
	v_mov_b32_e32 v109, v145
	v_pk_mul_f32 v[54:55], v[54:55], v[102:103] op_sel_hi:[1,0]
	v_pk_mul_f32 v[52:53], v[52:53], v[102:103] op_sel_hi:[1,0]
	v_pk_mul_f32 v[50:51], v[50:51], v[102:103] op_sel_hi:[1,0]
	v_pk_mul_f32 v[48:49], v[48:49], v[102:103] op_sel_hi:[1,0]
	v_add_co_u32_e32 v102, vcc, s16, v62
	global_store_dwordx4 v[62:63], v[106:109], off
	s_nop 1
	v_pk_mul_f32 v[106:107], v[76:77], v[106:107]
	v_addc_co_u32_e32 v103, vcc, 0, v63, vcc
	v_pk_fma_f32 v[56:57], v[64:65], v[56:57], v[106:107]
	global_store_dwordx4 v[102:103], v[52:55], off offset:2048
	v_pk_mul_f32 v[108:109], v[78:79], v[108:109]
	s_nop 0
	v_pk_fma_f32 v[52:53], v[68:69], v[52:53], v[56:57]
	v_pk_fma_f32 v[58:59], v[66:67], v[58:59], v[108:109]
	v_pk_add_f32 v[52:53], v[72:73], v[52:53]
	v_pk_fma_f32 v[54:55], v[70:71], v[54:55], v[58:59]
	v_mul_f32_e32 v56, 0xbfb8aa3b, v52
	v_exp_f32_e32 v56, v56
	v_pk_add_f32 v[54:55], v[74:75], v[54:55]
	v_add_f32_e32 v56, 1.0, v56
	v_rcp_f32_e32 v56, v56
	s_nop 0
	v_mul_f32_e32 v52, v52, v56
	v_mul_f32_e32 v48, v48, v52
	v_mul_f32_e32 v52, 0xbfb8aa3b, v53
	v_exp_f32_e32 v52, v52
	s_nop 0
	v_add_f32_e32 v52, 1.0, v52
	v_rcp_f32_e32 v52, v52
	s_nop 0
	v_mul_f32_e32 v52, v53, v52
	v_mul_f32_e32 v49, v49, v52
	v_cvt_pk_bf16_f32 v48, v48, v49
	v_mul_f32_e32 v49, 0xbfb8aa3b, v54
	v_exp_f32_e32 v49, v49
	s_nop 0
	v_add_f32_e32 v49, 1.0, v49
	v_rcp_f32_e32 v49, v49
	s_nop 0
	v_mul_f32_e32 v49, v54, v49
	v_mul_f32_e32 v49, v50, v49
	v_mul_f32_e32 v50, 0xbfb8aa3b, v55
	v_exp_f32_e32 v50, v50
	s_nop 0
	v_add_f32_e32 v50, 1.0, v50
	v_rcp_f32_e32 v50, v50
	s_nop 0
	v_mul_f32_e32 v50, v55, v50
	v_mul_f32_e32 v50, v51, v50
	v_cvt_pk_bf16_f32 v49, v49, v50
	v_mad_i64_i32 v[50:51], s[6:7], v104, s71, v[114:115]
	v_lshl_add_u64 v[52:53], v[50:51], 0, v[116:117]
	global_store_dwordx2 v[52:53], v[48:49], off
	v_add_u32_e32 v48, 0x2090, v229
	v_mad_i64_i32 v[48:49], s[6:7], v48, s71, v[114:115]
	v_add_u32_e32 v50, 32, v229
	v_lshl_add_u64 v[56:57], v[48:49], 0, v[116:117]
	v_mad_i64_i32 v[48:49], s[6:7], v50, s25, v[112:113]
	global_store_dwordx2 v[56:57], v[124:125], off
	v_lshl_add_u64 v[58:59], v[48:49], 0, v[118:119]
	v_mad_i64_i32 v[48:49], s[6:7], v50, s25, v[120:121]
	v_lshl_add_u64 v[104:105], v[110:111], 2, s[62:63]
	v_lshl_add_u64 v[54:55], v[48:49], 0, v[118:119]
	v_mov_b32_e32 v48, v216
	v_fmamk_f32 v48, v48, 0x3a000000, v212
	v_cmp_gt_f32_e32 vcc, s14, v48
	v_mul_f32_e32 v49, 0x4b800000, v48
	s_nop 0
	v_cndmask_b32_e32 v48, v48, v49, vcc
	v_rsq_f32_e32 v48, v48
	s_nop 0
	v_mul_f32_e32 v49, 0x45800000, v48
	v_cndmask_b32_e32 v108, v48, v49, vcc
	v_add_co_u32_e32 v106, vcc, s16, v58
	v_mov_b32_e32 v48, v146
	v_mov_b32_e32 v49, v147
	v_mov_b32_e32 v50, v148
	v_mov_b32_e32 v51, v149
	s_nop 0
	v_addc_co_u32_e32 v107, vcc, 0, v59, vcc
	v_mov_b32_e32 v126, v150
	v_mov_b32_e32 v127, v151
	v_mov_b32_e32 v128, v152
	v_mov_b32_e32 v129, v153
	v_pk_mul_f32 v[46:47], v[46:47], v[108:109] op_sel_hi:[1,0]
	v_pk_mul_f32 v[44:45], v[44:45], v[108:109] op_sel_hi:[1,0]
	v_pk_mul_f32 v[42:43], v[42:43], v[108:109] op_sel_hi:[1,0]
	v_pk_mul_f32 v[40:41], v[40:41], v[108:109] op_sel_hi:[1,0]
	v_add_co_u32_e32 v108, vcc, s16, v54
	global_store_dwordx4 v[54:55], v[126:129], off
	s_nop 1
	v_pk_mul_f32 v[126:127], v[76:77], v[126:127]
	v_addc_co_u32_e32 v109, vcc, 0, v55, vcc
	v_pk_fma_f32 v[48:49], v[64:65], v[48:49], v[126:127]
	global_store_dwordx4 v[108:109], v[44:47], off offset:2048
	v_pk_mul_f32 v[122:123], v[78:79], v[128:129]
	s_nop 0
	v_pk_fma_f32 v[44:45], v[68:69], v[44:45], v[48:49]
	v_pk_fma_f32 v[50:51], v[66:67], v[50:51], v[122:123]
	v_pk_add_f32 v[44:45], v[72:73], v[44:45]
	v_pk_fma_f32 v[46:47], v[70:71], v[46:47], v[50:51]
	v_mul_f32_e32 v48, 0xbfb8aa3b, v44
	v_exp_f32_e32 v48, v48
	v_pk_add_f32 v[46:47], v[74:75], v[46:47]
	v_add_f32_e32 v48, 1.0, v48
	v_rcp_f32_e32 v48, v48
	s_nop 0
	v_mul_f32_e32 v44, v44, v48
	v_mul_f32_e32 v40, v40, v44
	v_mul_f32_e32 v44, 0xbfb8aa3b, v45
	v_exp_f32_e32 v44, v44
	s_nop 0
	v_add_f32_e32 v44, 1.0, v44
	v_rcp_f32_e32 v44, v44
	s_nop 0
	v_mul_f32_e32 v44, v45, v44
	v_mul_f32_e32 v41, v41, v44
	v_cvt_pk_bf16_f32 v40, v40, v41
	v_mul_f32_e32 v41, 0xbfb8aa3b, v46
	v_exp_f32_e32 v41, v41
	v_add_u32_e32 v44, 0x2030, v229
	v_ashrrev_i32_e32 v45, 31, v44
	v_add_f32_e32 v41, 1.0, v41
	v_rcp_f32_e32 v41, v41
	s_nop 0
	v_mul_f32_e32 v41, v46, v41
	v_mul_f32_e32 v41, v42, v41
	v_mul_f32_e32 v42, 0xbfb8aa3b, v47
	v_exp_f32_e32 v42, v42
	s_nop 0
	v_add_f32_e32 v42, 1.0, v42
	v_rcp_f32_e32 v42, v42
	s_nop 0
	v_mul_f32_e32 v42, v47, v42
	v_mul_f32_e32 v42, v43, v42
	v_cvt_pk_bf16_f32 v41, v41, v42
	v_mad_i64_i32 v[42:43], s[6:7], v110, s71, v[114:115]
	v_lshl_add_u64 v[48:49], v[42:43], 0, v[116:117]
	global_store_dwordx2 v[48:49], v[40:41], off
	v_add_u32_e32 v40, 0x20a0, v229
	v_mad_i64_i32 v[40:41], s[6:7], v40, s71, v[114:115]
	v_add_u32_e32 v42, 48, v229
	v_lshl_add_u64 v[110:111], v[40:41], 0, v[116:117]
	v_mad_i64_i32 v[40:41], s[6:7], v42, s25, v[112:113]
; __device__ __forceinline__ unsigned cvt_pk_bf16(float lo, float hi) { unsigned r; asm volatile("v_cvt_pk_bf16_f32 %0, %1, %2" : "=v"(r) : "v"(lo), "v"(hi)); return r; }
; __device__ __forceinline__ float silu_f(float x) { return x * __builtin_amdgcn_rcpf(1.f + __expf(-x)); }
;     __device__ __forceinline__ void operator()(const f32x4 (&acc)[2][2][4][2], const pg8::Unit& u, int wr, int wc, int fr, int fq) const {
;     ...
;             for (int n = 0; n < 2; ++n) { const int cn = col + 4 * n;
;                 const f32x4 w0 = *(const f32x4*)(cw + cn), w1 = *(const f32x4*)(cw + DFF + cn), w2 = *(const f32x4*)(cw + 2 * DFF + cn), bb = *(const f32x4*)(cb + cn);
; #pragma unroll
;                 for (int m = 0; m < 4; ++m) { const int s = wr * 64 + m * 16 + fr; const float* sp = st_in + (size_t)s * 2 * DFF + cn; float* op = ffn_s + (size_t)s * 2 * DFF + cn;
;                     const float r1 = rsqrtf(SS[MP + s] * (1.f / DM) + EPS);
;                     const f32x4 s0 = *(const f32x4*)sp, s1 = *(const f32x4*)(sp + DFF), uu = acc[0][0][m][n] * r1, vv = acc[0][1][m][n] * r1;
;                     *(f32x4*)op = s1; *(f32x4*)(op + DFF) = uu;
;                     const f32x4 cu = s0 * w0 + s1 * w1 + uu * w2 + bb; u32x2 hw;
;                     hw.x = cvt_pk_bf16(silu_f(cu[0]) * vv[0], silu_f(cu[1]) * vv[1]); hw.y = cvt_pk_bf16(silu_f(cu[2]) * vv[2], silu_f(cu[3]) * vv[3]);
;                     *(u32x2*)(H + (size_t)(MP + s) * DFF + cn) = hw; *(u32x2*)(H + (size_t)(MP + 128 + s) * DFF + cn) = (u32x2){0u, 0u}; }
	v_lshl_add_u64 v[112:113], v[40:41], 0, v[118:119]
	v_mad_i64_i32 v[40:41], s[6:7], v42, s25, v[120:121]
	global_store_dwordx2 v[110:111], v[124:125], off
	v_lshl_add_u64 v[50:51], v[40:41], 0, v[118:119]
	v_lshl_add_u64 v[118:119], v[44:45], 2, s[62:63]
	v_mov_b32_e32 v40, v219
	v_fmamk_f32 v40, v40, 0x3a000000, v212
	v_cmp_gt_f32_e32 vcc, s14, v40
	v_mul_f32_e32 v41, 0x4b800000, v40
	s_nop 0
	v_cndmask_b32_e32 v40, v40, v41, vcc
	v_rsq_f32_e32 v40, v40
	s_nop 0
	v_mul_f32_e32 v41, 0x45800000, v40
	v_cndmask_b32_e32 v46, v40, v41, vcc
	v_add_co_u32_e32 v120, vcc, s16, v112
	v_mov_b32_e32 v40, v154
	v_mov_b32_e32 v41, v155
	v_mov_b32_e32 v42, v156
	v_mov_b32_e32 v43, v157
	s_nop 0
	v_addc_co_u32_e32 v121, vcc, 0, v113, vcc
	v_mov_b32_e32 v126, v160
	v_mov_b32_e32 v127, v161
	v_mov_b32_e32 v128, v162
	v_mov_b32_e32 v129, v163
	v_add_co_u32_e32 v122, vcc, s16, v50
	v_pk_mul_f32 v[38:39], v[38:39], v[46:47] op_sel_hi:[1,0]
	v_pk_mul_f32 v[36:37], v[36:37], v[46:47] op_sel_hi:[1,0]
	v_addc_co_u32_e32 v123, vcc, 0, v51, vcc
	global_store_dwordx4 v[122:123], v[36:39], off offset:2048
	v_pk_mul_f32 v[32:33], v[32:33], v[46:47] op_sel_hi:[1,0]
	v_pk_mul_f32 v[34:35], v[34:35], v[46:47] op_sel_hi:[1,0]
	v_pk_mul_f32 v[76:77], v[76:77], v[126:127]
	s_nop 0
	v_pk_fma_f32 v[40:41], v[64:65], v[40:41], v[76:77]
	v_pk_mul_f32 v[46:47], v[78:79], v[128:129]
	v_pk_fma_f32 v[36:37], v[68:69], v[36:37], v[40:41]
	v_pk_fma_f32 v[42:43], v[66:67], v[42:43], v[46:47]
	v_pk_add_f32 v[36:37], v[72:73], v[36:37]
	v_pk_fma_f32 v[38:39], v[70:71], v[38:39], v[42:43]
	v_mul_f32_e32 v40, 0xbfb8aa3b, v36
	v_exp_f32_e32 v40, v40
	v_pk_add_f32 v[38:39], v[74:75], v[38:39]
	global_store_dwordx4 v[50:51], v[126:129], off
	v_add_f32_e32 v40, 1.0, v40
	v_rcp_f32_e32 v40, v40
	s_nop 0
	v_mul_f32_e32 v36, v36, v40
	v_mul_f32_e32 v32, v32, v36
	v_mul_f32_e32 v36, 0xbfb8aa3b, v37
	v_exp_f32_e32 v36, v36
	s_nop 0
	v_add_f32_e32 v36, 1.0, v36
	v_rcp_f32_e32 v36, v36
	s_nop 0
	v_mul_f32_e32 v36, v37, v36
	v_mul_f32_e32 v33, v33, v36
	v_cvt_pk_bf16_f32 v32, v32, v33
	v_mul_f32_e32 v33, 0xbfb8aa3b, v38
	v_exp_f32_e32 v33, v33
	s_nop 0
	v_add_f32_e32 v33, 1.0, v33
	v_rcp_f32_e32 v33, v33
	s_nop 0
	v_mul_f32_e32 v33, v38, v33
	v_mul_f32_e32 v33, v34, v33
	v_mul_f32_e32 v34, 0xbfb8aa3b, v39
	v_exp_f32_e32 v34, v34
	s_nop 0
	v_add_f32_e32 v34, 1.0, v34
	v_rcp_f32_e32 v34, v34
	s_nop 0
	v_mul_f32_e32 v34, v39, v34
	v_mul_f32_e32 v34, v35, v34
	v_cvt_pk_bf16_f32 v33, v33, v34
	v_mad_i64_i32 v[34:35], s[6:7], v44, s71, v[114:115]
	v_lshl_add_u64 v[64:65], v[34:35], 0, v[116:117]
	global_store_dwordx2 v[64:65], v[32:33], off
	v_add_u32_e32 v32, 0x20b0, v229
	v_mad_i64_i32 v[32:33], s[6:7], v32, s71, v[114:115]
	v_lshl_add_u64 v[66:67], v[32:33], 0, v[116:117]
	v_or_b32_e32 v32, 4, v186
	v_ashrrev_i32_e32 v33, 31, v32
	global_store_dwordx2 v[66:67], v[124:125], off
	v_lshlrev_b64 v[32:33], 2, v[32:33]
	v_lshl_add_u64 v[34:35], s[34:35], 0, v[32:33]
	v_lshl_add_u64 v[32:33], s[22:23], 0, v[32:33]
	global_load_dwordx4 v[36:39], v[100:101], off offset:16
	global_load_dwordx4 v[44:47], v[34:35], off
	global_load_dwordx4 v[40:43], v[32:33], off
	s_nop 0
	global_load_dwordx4 v[32:35], v[98:99], off offset:16
	v_mov_b32_e32 v68, v214
	s_waitcnt vmcnt(0)
	v_fmamk_f32 v68, v68, 0x3a000000, v212
	v_cmp_gt_f32_e32 vcc, s14, v68
	v_mul_f32_e32 v69, 0x4b800000, v68
	s_nop 0
	v_cndmask_b32_e32 v68, v68, v69, vcc
	v_rsq_f32_e32 v68, v68
	s_nop 0
	v_mul_f32_e32 v69, 0x45800000, v68
	v_cndmask_b32_e32 v76, v68, v69, vcc
	v_mov_b32_e32 v68, v164
	v_mov_b32_e32 v69, v165
	v_mov_b32_e32 v70, v166
	v_mov_b32_e32 v71, v167
	v_mov_b32_e32 v72, v188
	v_mov_b32_e32 v73, v189
	v_mov_b32_e32 v74, v190
	v_mov_b32_e32 v75, v191
	v_pk_mul_f32 v[30:31], v[30:31], v[76:77] op_sel_hi:[1,0]
	v_pk_mul_f32 v[28:29], v[28:29], v[76:77] op_sel_hi:[1,0]
	global_store_dwordx4 v[80:81], v[72:75], off offset:16
	global_store_dwordx4 v[60:61], v[28:31], off offset:2064
	s_nop 0
	v_pk_mul_f32 v[72:73], v[44:45], v[72:73]
	v_pk_mul_f32 v[60:61], v[46:47], v[74:75]
	v_pk_fma_f32 v[68:69], v[36:37], v[68:69], v[72:73]
	v_pk_fma_f32 v[60:61], v[38:39], v[70:71], v[60:61]
	v_pk_fma_f32 v[28:29], v[40:41], v[28:29], v[68:69]
	v_pk_fma_f32 v[30:31], v[42:43], v[30:31], v[60:61]
	v_pk_add_f32 v[28:29], v[32:33], v[28:29]
	v_pk_mul_f32 v[24:25], v[24:25], v[76:77] op_sel_hi:[1,0]
	v_mul_f32_e32 v60, 0xbfb8aa3b, v28
	v_exp_f32_e32 v60, v60
	v_pk_add_f32 v[30:31], v[34:35], v[30:31]
	v_pk_mul_f32 v[26:27], v[26:27], v[76:77] op_sel_hi:[1,0]
	v_add_f32_e32 v60, 1.0, v60
	v_rcp_f32_e32 v60, v60
	s_nop 0
	v_mul_f32_e32 v28, v28, v60
	v_mul_f32_e32 v24, v24, v28
	v_mul_f32_e32 v28, 0xbfb8aa3b, v29
	v_exp_f32_e32 v28, v28
	s_nop 0
	v_add_f32_e32 v28, 1.0, v28
	v_rcp_f32_e32 v28, v28
	s_nop 0
	v_mul_f32_e32 v28, v29, v28
	v_mul_f32_e32 v25, v25, v28
	v_cvt_pk_bf16_f32 v24, v24, v25
	v_mul_f32_e32 v25, 0xbfb8aa3b, v30
	v_exp_f32_e32 v25, v25
	s_nop 0
	v_add_f32_e32 v25, 1.0, v25
	v_rcp_f32_e32 v25, v25
	s_nop 0
	v_mul_f32_e32 v25, v30, v25
	v_mul_f32_e32 v25, v26, v25
	v_mul_f32_e32 v26, 0xbfb8aa3b, v31
	v_exp_f32_e32 v26, v26
	s_nop 0
	v_add_f32_e32 v26, 1.0, v26
	v_rcp_f32_e32 v26, v26
	s_nop 0
	v_mul_f32_e32 v26, v31, v26
	v_mul_f32_e32 v26, v27, v26
	v_cvt_pk_bf16_f32 v25, v25, v26
	global_store_dwordx2 v[84:85], v[24:25], off offset:8
	global_store_dwordx2 v[90:91], v[124:125], off offset:8
	v_mov_b32_e32 v24, v215
	v_fmamk_f32 v24, v24, 0x3a000000, v212
	v_cmp_gt_f32_e32 vcc, s14, v24
	v_mul_f32_e32 v25, 0x4b800000, v24
	s_nop 0
	v_cndmask_b32_e32 v24, v24, v25, vcc
	v_rsq_f32_e32 v24, v24
	s_nop 0
	v_mul_f32_e32 v25, 0x45800000, v24
; __device__ __forceinline__ unsigned cvt_pk_bf16(float lo, float hi) { unsigned r; asm volatile("v_cvt_pk_bf16_f32 %0, %1, %2" : "=v"(r) : "v"(lo), "v"(hi)); return r; }
; __device__ __forceinline__ float silu_f(float x) { return x * __builtin_amdgcn_rcpf(1.f + __expf(-x)); }
;     __device__ __forceinline__ void operator()(const f32x4 (&acc)[2][2][4][2], const pg8::Unit& u, int wr, int wc, int fr, int fq) const {
;     ...
;                 for (int m = 0; m < 4; ++m) { const int s = wr * 64 + m * 16 + fr; const float* sp = st_in + (size_t)s * 2 * DFF + cn; float* op = ffn_s + (size_t)s * 2 * DFF + cn;
;                     const float r1 = rsqrtf(SS[MP + s] * (1.f / DM) + EPS);
;                     const f32x4 s0 = *(const f32x4*)sp, s1 = *(const f32x4*)(sp + DFF), uu = acc[0][0][m][n] * r1, vv = acc[0][1][m][n] * r1;
;                     *(f32x4*)op = s1; *(f32x4*)(op + DFF) = uu;
;                     const f32x4 cu = s0 * w0 + s1 * w1 + uu * w2 + bb; u32x2 hw;
;                     hw.x = cvt_pk_bf16(silu_f(cu[0]) * vv[0], silu_f(cu[1]) * vv[1]); hw.y = cvt_pk_bf16(silu_f(cu[2]) * vv[2], silu_f(cu[3]) * vv[3]);
;                     *(u32x2*)(H + (size_t)(MP + s) * DFF + cn) = hw; *(u32x2*)(H + (size_t)(MP + 128 + s) * DFF + cn) = (u32x2){0u, 0u}; }
;                 asm volatile("" ::: "memory"); }
;             return;
	v_cndmask_b32_e32 v60, v24, v25, vcc
	v_mov_b32_e32 v24, v192
	v_mov_b32_e32 v25, v193
	v_mov_b32_e32 v26, v194
	v_mov_b32_e32 v27, v195
	v_mov_b32_e32 v28, v196
	v_mov_b32_e32 v29, v197
	v_mov_b32_e32 v30, v198
	v_mov_b32_e32 v31, v199
	v_pk_mul_f32 v[22:23], v[22:23], v[60:61] op_sel_hi:[1,0]
	v_pk_mul_f32 v[20:21], v[20:21], v[60:61] op_sel_hi:[1,0]
	global_store_dwordx4 v[62:63], v[28:31], off offset:16
	global_store_dwordx4 v[102:103], v[20:23], off offset:2064
	s_nop 0
	v_pk_mul_f32 v[28:29], v[44:45], v[28:29]
	v_pk_mul_f32 v[16:17], v[16:17], v[60:61] op_sel_hi:[1,0]
	v_pk_fma_f32 v[24:25], v[36:37], v[24:25], v[28:29]
	v_pk_mul_f32 v[30:31], v[46:47], v[30:31]
	v_pk_fma_f32 v[20:21], v[40:41], v[20:21], v[24:25]
	v_pk_fma_f32 v[26:27], v[38:39], v[26:27], v[30:31]
	v_pk_add_f32 v[20:21], v[32:33], v[20:21]
	v_pk_fma_f32 v[22:23], v[42:43], v[22:23], v[26:27]
	v_mul_f32_e32 v24, 0xbfb8aa3b, v20
	v_exp_f32_e32 v24, v24
	v_pk_add_f32 v[22:23], v[34:35], v[22:23]
	v_pk_mul_f32 v[18:19], v[18:19], v[60:61] op_sel_hi:[1,0]
	v_add_f32_e32 v24, 1.0, v24
	v_rcp_f32_e32 v24, v24
	s_nop 0
	v_mul_f32_e32 v20, v20, v24
	v_mul_f32_e32 v16, v16, v20
	v_mul_f32_e32 v20, 0xbfb8aa3b, v21
	v_exp_f32_e32 v20, v20
	s_nop 0
	v_add_f32_e32 v20, 1.0, v20
	v_rcp_f32_e32 v20, v20
	s_nop 0
	v_mul_f32_e32 v20, v21, v20
	v_mul_f32_e32 v17, v17, v20
	v_cvt_pk_bf16_f32 v16, v16, v17
	v_mul_f32_e32 v17, 0xbfb8aa3b, v22
	v_exp_f32_e32 v17, v17
	s_nop 0
	v_add_f32_e32 v17, 1.0, v17
	v_rcp_f32_e32 v17, v17
	s_nop 0
	v_mul_f32_e32 v17, v22, v17
	v_mul_f32_e32 v17, v18, v17
	v_mul_f32_e32 v18, 0xbfb8aa3b, v23
	v_exp_f32_e32 v18, v18
	s_nop 0
	v_add_f32_e32 v18, 1.0, v18
	v_rcp_f32_e32 v18, v18
	s_nop 0
	v_mul_f32_e32 v18, v23, v18
	v_mul_f32_e32 v18, v19, v18
	v_cvt_pk_bf16_f32 v17, v17, v18
	global_store_dwordx2 v[52:53], v[16:17], off offset:8
	global_store_dwordx2 v[56:57], v[124:125], off offset:8
	v_mov_b32_e32 v16, v216
	v_fmamk_f32 v16, v16, 0x3a000000, v212
	v_cmp_gt_f32_e32 vcc, s14, v16
	v_mul_f32_e32 v17, 0x4b800000, v16
	s_nop 0
	v_cndmask_b32_e32 v16, v16, v17, vcc
	v_rsq_f32_e32 v16, v16
	s_nop 0
	v_mul_f32_e32 v17, 0x45800000, v16
	v_cndmask_b32_e32 v24, v16, v17, vcc
	v_mov_b32_e32 v16, v200
	v_mov_b32_e32 v17, v201
	v_mov_b32_e32 v18, v202
	v_mov_b32_e32 v19, v203
	v_mov_b32_e32 v20, v204
	v_mov_b32_e32 v21, v205
	v_mov_b32_e32 v22, v206
	v_mov_b32_e32 v23, v207
	v_pk_mul_f32 v[14:15], v[14:15], v[24:25] op_sel_hi:[1,0]
	v_pk_mul_f32 v[12:13], v[12:13], v[24:25] op_sel_hi:[1,0]
	global_store_dwordx4 v[54:55], v[20:23], off offset:16
	global_store_dwordx4 v[108:109], v[12:15], off offset:2064
	s_nop 0
	v_pk_mul_f32 v[20:21], v[44:45], v[20:21]
	v_pk_mul_f32 v[8:9], v[8:9], v[24:25] op_sel_hi:[1,0]
	v_pk_fma_f32 v[16:17], v[36:37], v[16:17], v[20:21]
	v_pk_mul_f32 v[22:23], v[46:47], v[22:23]
	v_pk_fma_f32 v[12:13], v[40:41], v[12:13], v[16:17]
	v_pk_fma_f32 v[18:19], v[38:39], v[18:19], v[22:23]
	v_pk_add_f32 v[12:13], v[32:33], v[12:13]
	v_pk_fma_f32 v[14:15], v[42:43], v[14:15], v[18:19]
	v_mul_f32_e32 v16, 0xbfb8aa3b, v12
	v_exp_f32_e32 v16, v16
	v_pk_add_f32 v[14:15], v[34:35], v[14:15]
	v_pk_mul_f32 v[10:11], v[10:11], v[24:25] op_sel_hi:[1,0]
	v_add_f32_e32 v16, 1.0, v16
	v_rcp_f32_e32 v16, v16
	s_nop 0
	v_mul_f32_e32 v12, v12, v16
	v_mul_f32_e32 v8, v8, v12
	v_mul_f32_e32 v12, 0xbfb8aa3b, v13
	v_exp_f32_e32 v12, v12
	s_nop 0
	v_add_f32_e32 v12, 1.0, v12
	v_rcp_f32_e32 v12, v12
	s_nop 0
	v_mul_f32_e32 v12, v13, v12
	v_mul_f32_e32 v9, v9, v12
	v_cvt_pk_bf16_f32 v8, v8, v9
	v_mul_f32_e32 v9, 0xbfb8aa3b, v14
	v_exp_f32_e32 v9, v9
	s_nop 0
	v_add_f32_e32 v9, 1.0, v9
	v_rcp_f32_e32 v9, v9
	s_nop 0
	v_mul_f32_e32 v9, v14, v9
	v_mul_f32_e32 v9, v10, v9
	v_mul_f32_e32 v10, 0xbfb8aa3b, v15
	v_exp_f32_e32 v10, v10
	s_nop 0
	v_add_f32_e32 v10, 1.0, v10
	v_rcp_f32_e32 v10, v10
	s_nop 0
	v_mul_f32_e32 v10, v15, v10
	v_mul_f32_e32 v10, v11, v10
	v_cvt_pk_bf16_f32 v9, v9, v10
	global_store_dwordx2 v[48:49], v[8:9], off offset:8
	global_store_dwordx2 v[110:111], v[124:125], off offset:8
	v_mov_b32_e32 v8, v219
	v_fmamk_f32 v8, v8, 0x3a000000, v212
	v_cmp_gt_f32_e32 vcc, s14, v8
	v_mul_f32_e32 v9, 0x4b800000, v8
	s_nop 0
	v_cndmask_b32_e32 v8, v8, v9, vcc
	v_rsq_f32_e32 v8, v8
	s_nop 0
	v_mul_f32_e32 v9, 0x45800000, v8
	v_cndmask_b32_e32 v16, v8, v9, vcc
	v_mov_b32_e32 v8, v248
	v_mov_b32_e32 v9, v249
	v_mov_b32_e32 v10, v250
	v_mov_b32_e32 v11, v251
	v_mov_b32_e32 v12, v252
	v_mov_b32_e32 v13, v253
	v_mov_b32_e32 v14, v254
	v_mov_b32_e32 v15, v255
	v_pk_mul_f32 v[6:7], v[6:7], v[16:17] op_sel_hi:[1,0]
	v_pk_mul_f32 v[4:5], v[4:5], v[16:17] op_sel_hi:[1,0]
	global_store_dwordx4 v[50:51], v[12:15], off offset:16
	global_store_dwordx4 v[122:123], v[4:7], off offset:2064
	s_nop 0
	v_pk_mul_f32 v[12:13], v[44:45], v[12:13]
	v_pk_mul_f32 v[0:1], v[0:1], v[16:17] op_sel_hi:[1,0]
	v_pk_fma_f32 v[8:9], v[36:37], v[8:9], v[12:13]
	v_pk_mul_f32 v[14:15], v[46:47], v[14:15]
	v_pk_fma_f32 v[4:5], v[40:41], v[4:5], v[8:9]
	v_pk_fma_f32 v[10:11], v[38:39], v[10:11], v[14:15]
	v_pk_add_f32 v[4:5], v[32:33], v[4:5]
	v_pk_fma_f32 v[6:7], v[42:43], v[6:7], v[10:11]
	v_mul_f32_e32 v8, 0xbfb8aa3b, v4
	v_exp_f32_e32 v8, v8
	v_pk_add_f32 v[6:7], v[34:35], v[6:7]
	v_pk_mul_f32 v[2:3], v[2:3], v[16:17] op_sel_hi:[1,0]
	v_add_f32_e32 v8, 1.0, v8
	v_rcp_f32_e32 v8, v8
	s_nop 0
	v_mul_f32_e32 v4, v4, v8
	v_mul_f32_e32 v0, v0, v4
	v_mul_f32_e32 v4, 0xbfb8aa3b, v5
	v_exp_f32_e32 v4, v4
	s_nop 0
	v_add_f32_e32 v4, 1.0, v4
	v_rcp_f32_e32 v4, v4
	s_nop 0
	v_mul_f32_e32 v4, v5, v4
	v_mul_f32_e32 v1, v1, v4
	v_cvt_pk_bf16_f32 v0, v0, v1
	v_mul_f32_e32 v1, 0xbfb8aa3b, v6
	v_exp_f32_e32 v1, v1
	s_nop 0
	v_add_f32_e32 v1, 1.0, v1
	v_rcp_f32_e32 v1, v1
	s_nop 0
	v_mul_f32_e32 v1, v6, v1
	v_mul_f32_e32 v1, v2, v1
	v_mul_f32_e32 v2, 0xbfb8aa3b, v7
	v_exp_f32_e32 v2, v2
	s_nop 0
	v_add_f32_e32 v2, 1.0, v2
	v_rcp_f32_e32 v2, v2
	s_nop 0
	v_mul_f32_e32 v2, v7, v2
	v_mul_f32_e32 v2, v3, v2
	v_cvt_pk_bf16_f32 v1, v1, v2
	global_store_dwordx2 v[64:65], v[0:1], off offset:8
	global_store_dwordx2 v[66:67], v[124:125], off offset:8
	s_andn2_b64 vcc, exec, s[58:59]
	s_mov_b64 s[6:7], -1
	s_cbranch_vccnz .LBB0_780
